# hyena filter images: the 32 f_w3 fragment loads requested together (address temporaries renamed), conversions afterwards in the same order
# speedup vs baseline: 1.0019x; 1.0019x over previous
.LBB0_256:
	v_bfe_u32 v2, v48, 6, 1
	v_lshlrev_b32_e32 v3, 5, v48
	v_bfe_u32 v38, v48, 7, 1
	v_and_or_b32 v39, v3, s38, v49
	v_lshlrev_b32_e32 v3, 11, v2
	v_lshl_or_b32 v3, v38, 12, v3
	v_or3_b32 v3, v52, v3, v39
	v_lshlrev_b32_e32 v34, 2, v3
	v_lshl_add_u64 v[4:5], s[22:23], 0, v[34:35]
	v_add_co_u32_e32 v116, vcc, 0x8000, v4
	s_movk_i32 s0, 0x700
	s_nop 0
	v_addc_co_u32_e32 v117, vcc, 0, v5, vcc
	v_add_co_u32_e32 v118, vcc, 0x18000, v4
	s_nop 1
	v_addc_co_u32_e32 v119, vcc, 0, v5, vcc
	v_add_co_u32_e32 v120, vcc, 0x10000, v4
	s_nop 1
	v_addc_co_u32_e32 v121, vcc, 0, v5, vcc
	v_add_co_u32_e32 v122, vcc, 0x28000, v4
	s_nop 1
	v_addc_co_u32_e32 v123, vcc, 0, v5, vcc
	v_add_co_u32_e32 v124, vcc, 0x20000, v4
	s_nop 1
	v_addc_co_u32_e32 v125, vcc, 0, v5, vcc
	v_add_co_u32_e32 v126, vcc, 0x38000, v4
	s_nop 1
	v_addc_co_u32_e32 v127, vcc, 0, v5, vcc
	v_add_co_u32_e32 v128, vcc, 0x30000, v4
	s_nop 1
	v_addc_co_u32_e32 v129, vcc, 0, v5, vcc
	global_load_dword v131, v[116:117], off
	global_load_dword v132, v34, s[22:23]
	global_load_dword v133, v[118:119], off
	global_load_dword v135, v[120:121], off
	global_load_dword v136, v[122:123], off
	global_load_dword v137, v[124:125], off
	global_load_dword v138, v[126:127], off
	global_load_dword v139, v[128:129], off
	v_add_co_u32_e32 v140, vcc, 0x88000, v4
	s_nop 1
	v_addc_co_u32_e32 v141, vcc, 0, v5, vcc
	v_add_co_u32_e32 v142, vcc, 0x80000, v4
	s_nop 1
	v_addc_co_u32_e32 v143, vcc, 0, v5, vcc
	v_add_co_u32_e32 v144, vcc, 0x98000, v4
	s_nop 1
	v_addc_co_u32_e32 v145, vcc, 0, v5, vcc
	v_add_co_u32_e32 v146, vcc, s37, v4
	s_nop 1
	v_addc_co_u32_e32 v147, vcc, 0, v5, vcc
	v_add_co_u32_e32 v148, vcc, 0xa8000, v4
	s_nop 1
	v_addc_co_u32_e32 v149, vcc, 0, v5, vcc
	v_add_co_u32_e32 v150, vcc, 0xa0000, v4
	s_nop 1
	v_addc_co_u32_e32 v151, vcc, 0, v5, vcc
	v_add_co_u32_e32 v152, vcc, 0xb8000, v4
	s_nop 1
	v_addc_co_u32_e32 v153, vcc, 0, v5, vcc
	v_add_co_u32_e32 v154, vcc, 0xb0000, v4
	s_nop 1
	v_addc_co_u32_e32 v155, vcc, 0, v5, vcc
	global_load_dword v157, v[140:141], off
	global_load_dword v158, v[142:143], off
	global_load_dword v159, v[144:145], off
	global_load_dword v160, v[146:147], off
	global_load_dword v161, v[148:149], off
	global_load_dword v162, v[150:151], off
	global_load_dword v164, v[152:153], off
	s_nop 0
	global_load_dword v167, v[154:155], off
	v_add_co_u32_e32 v168, vcc, 0x108000, v4
	s_nop 1
	v_addc_co_u32_e32 v169, vcc, 0, v5, vcc
	v_add_co_u32_e32 v170, vcc, 0x100000, v4
	s_nop 1
	v_addc_co_u32_e32 v171, vcc, 0, v5, vcc
	v_add_co_u32_e32 v172, vcc, 0x118000, v4
	s_nop 1
	v_addc_co_u32_e32 v173, vcc, 0, v5, vcc
	v_add_co_u32_e32 v174, vcc, 0x110000, v4
	s_nop 1
	v_addc_co_u32_e32 v175, vcc, 0, v5, vcc
	v_add_co_u32_e32 v176, vcc, 0x128000, v4
	s_nop 1
	v_addc_co_u32_e32 v177, vcc, 0, v5, vcc
	v_add_co_u32_e32 v178, vcc, 0x120000, v4
	s_nop 1
	v_addc_co_u32_e32 v179, vcc, 0, v5, vcc
	v_add_co_u32_e32 v180, vcc, 0x138000, v4
	s_nop 1
	v_addc_co_u32_e32 v181, vcc, 0, v5, vcc
	v_add_co_u32_e32 v182, vcc, 0x130000, v4
	s_nop 1
	v_addc_co_u32_e32 v183, vcc, 0, v5, vcc
	global_load_dword v185, v[168:169], off
	global_load_dword v186, v[170:171], off
	global_load_dword v187, v[172:173], off
	global_load_dword v188, v[174:175], off
	global_load_dword v190, v[176:177], off
	global_load_dword v191, v[178:179], off
	global_load_dword v192, v[180:181], off
	s_nop 0
	global_load_dword v195, v[182:183], off
	v_add_co_u32_e32 v196, vcc, 0x188000, v4
	s_nop 1
	v_addc_co_u32_e32 v197, vcc, 0, v5, vcc
	v_add_co_u32_e32 v198, vcc, 0x180000, v4
	s_nop 1
	v_addc_co_u32_e32 v199, vcc, 0, v5, vcc
	v_add_co_u32_e32 v200, vcc, 0x198000, v4
	s_nop 1
	v_addc_co_u32_e32 v201, vcc, 0, v5, vcc
	v_add_co_u32_e32 v202, vcc, 0x190000, v4
	s_nop 1
	v_addc_co_u32_e32 v203, vcc, 0, v5, vcc
	v_add_co_u32_e32 v204, vcc, 0x1a8000, v4
	s_nop 1
	v_addc_co_u32_e32 v205, vcc, 0, v5, vcc
	v_add_co_u32_e32 v206, vcc, 0x1a0000, v4
	s_nop 1
	v_addc_co_u32_e32 v207, vcc, 0, v5, vcc
	v_add_co_u32_e32 v208, vcc, 0x1b8000, v4
	s_nop 1
	v_addc_co_u32_e32 v209, vcc, 0, v5, vcc
	v_add_co_u32_e32 v216, vcc, 0x1b0000, v4
	s_nop 1
	v_addc_co_u32_e32 v217, vcc, 0, v5, vcc
	global_load_dword v219, v[196:197], off
	s_nop 0
	global_load_dword v220, v[198:199], off
	global_load_dword v221, v[200:201], off
	s_nop 0
	global_load_dword v222, v[202:203], off
	global_load_dword v223, v[204:205], off
	global_load_dword v224, v[206:207], off
	global_load_dword v225, v[208:209], off
	s_nop 0
	global_load_dword v226, v[216:217], off
	v_lshlrev_b32_e32 v5, 2, v39
	v_lshl_or_b32 v5, v38, 13, v5
	s_waitcnt vmcnt(30)
	v_cvt_pk_bf16_f32 v18, v132, v131
	s_waitcnt vmcnt(28)
	v_cvt_pk_bf16_f32 v19, v135, v133
	s_waitcnt vmcnt(26)
	v_cvt_pk_bf16_f32 v20, v137, v136
	s_waitcnt vmcnt(24)
	v_cvt_pk_bf16_f32 v21, v139, v138
	s_waitcnt vmcnt(22)
	v_cvt_pk_bf16_f32 v22, v158, v157
	s_waitcnt vmcnt(20)
	v_cvt_pk_bf16_f32 v23, v160, v159
	s_waitcnt vmcnt(18)
	v_cvt_pk_bf16_f32 v24, v162, v161
	s_waitcnt vmcnt(16)
	v_cvt_pk_bf16_f32 v25, v167, v164
	s_waitcnt vmcnt(14)
	v_cvt_pk_bf16_f32 v26, v186, v185
	s_waitcnt vmcnt(12)
	v_cvt_pk_bf16_f32 v27, v188, v187
	s_waitcnt vmcnt(10)
	v_cvt_pk_bf16_f32 v28, v191, v190
	s_waitcnt vmcnt(8)
	v_cvt_pk_bf16_f32 v29, v195, v192
	s_waitcnt vmcnt(6)
	v_cvt_pk_bf16_f32 v30, v220, v219
	s_waitcnt vmcnt(4)
	v_cvt_pk_bf16_f32 v31, v222, v221
	s_waitcnt vmcnt(2)
	v_cvt_pk_bf16_f32 v32, v224, v223
	s_waitcnt vmcnt(0)
	v_cvt_pk_bf16_f32 v33, v226, v225
	global_load_dword v3, v5, s[24:25]
	global_load_dword v54, v5, s[26:27]
	v_lshrrev_b32_e32 v4, 6, v48
	v_lshlrev_b32_e32 v5, 24, v38
	v_lshl_or_b32 v34, v39, 13, v5
	v_and_b32_e32 v5, 0xffffff00, v48
	v_bitop3_b32 v6, v4, 1, v50 bitop3:0xc8
	v_cmp_eq_u32_e32 vcc, s0, v5
	v_cmp_eq_u32_e64 s[0:1], 0, v6
	v_lshl_add_u64 v[38:39], s[28:29], 0, v[34:35]
	s_and_b64 s[34:35], vcc, s[0:1]
	s_and_saveexec_b64 s[0:1], s[34:35]
	s_cbranch_execz .LBB0_258
	global_store_short v[38:39], v35, off

.LBB0_300:
	v_bfe_u32 v2, v48, 6, 1
	v_lshlrev_b32_e32 v3, 5, v48
	v_bfe_u32 v40, v48, 7, 1
	v_and_or_b32 v41, v3, s38, v49
	v_lshlrev_b32_e32 v3, 11, v2
	v_lshl_or_b32 v3, v40, 12, v3
	v_or3_b32 v3, v52, v3, v41
	v_lshlrev_b32_e32 v34, 2, v3
	v_lshl_add_u64 v[4:5], s[42:43], 0, v[34:35]
	v_add_co_u32_e32 v116, vcc, 0x8000, v4
	s_nop 1
	v_addc_co_u32_e32 v117, vcc, 0, v5, vcc
	v_add_co_u32_e32 v118, vcc, 0x18000, v4
	s_nop 1
	v_addc_co_u32_e32 v119, vcc, 0, v5, vcc
	v_add_co_u32_e32 v120, vcc, 0x10000, v4
	s_nop 1
	v_addc_co_u32_e32 v121, vcc, 0, v5, vcc
	v_add_co_u32_e32 v122, vcc, 0x28000, v4
	s_nop 1
	v_addc_co_u32_e32 v123, vcc, 0, v5, vcc
	v_add_co_u32_e32 v124, vcc, 0x20000, v4
	s_nop 1
	v_addc_co_u32_e32 v125, vcc, 0, v5, vcc
	v_add_co_u32_e32 v126, vcc, 0x38000, v4
	s_nop 1
	v_addc_co_u32_e32 v127, vcc, 0, v5, vcc
	v_add_co_u32_e32 v128, vcc, 0x30000, v4
	s_nop 1
	v_addc_co_u32_e32 v129, vcc, 0, v5, vcc
	global_load_dword v131, v[116:117], off
	global_load_dword v132, v34, s[42:43]
	global_load_dword v133, v[118:119], off
	global_load_dword v135, v[120:121], off
	global_load_dword v136, v[122:123], off
	global_load_dword v137, v[124:125], off
	global_load_dword v138, v[126:127], off
	global_load_dword v139, v[128:129], off
	v_add_co_u32_e32 v140, vcc, 0x88000, v4
	s_nop 1
	v_addc_co_u32_e32 v141, vcc, 0, v5, vcc
	v_add_co_u32_e32 v142, vcc, 0x80000, v4
	s_nop 1
	v_addc_co_u32_e32 v143, vcc, 0, v5, vcc
	v_add_co_u32_e32 v144, vcc, 0x98000, v4
	s_nop 1
	v_addc_co_u32_e32 v145, vcc, 0, v5, vcc
	v_add_co_u32_e32 v146, vcc, s37, v4
	s_nop 1
	v_addc_co_u32_e32 v147, vcc, 0, v5, vcc
	v_add_co_u32_e32 v148, vcc, 0xa8000, v4
	s_nop 1
	v_addc_co_u32_e32 v149, vcc, 0, v5, vcc
	v_add_co_u32_e32 v150, vcc, 0xa0000, v4
	s_nop 1
	v_addc_co_u32_e32 v151, vcc, 0, v5, vcc
	v_add_co_u32_e32 v152, vcc, 0xb8000, v4
	s_nop 1
	v_addc_co_u32_e32 v153, vcc, 0, v5, vcc
	v_add_co_u32_e32 v154, vcc, 0xb0000, v4
	s_nop 1
	v_addc_co_u32_e32 v155, vcc, 0, v5, vcc
	global_load_dword v157, v[140:141], off
	global_load_dword v158, v[142:143], off
	global_load_dword v159, v[144:145], off
	global_load_dword v160, v[146:147], off
	global_load_dword v161, v[148:149], off
	global_load_dword v162, v[150:151], off
	global_load_dword v164, v[152:153], off
	s_nop 0
	global_load_dword v167, v[154:155], off
	v_add_co_u32_e32 v168, vcc, 0x108000, v4
	s_nop 1
	v_addc_co_u32_e32 v169, vcc, 0, v5, vcc
	v_add_co_u32_e32 v170, vcc, 0x100000, v4
	s_nop 1
	v_addc_co_u32_e32 v171, vcc, 0, v5, vcc
	v_add_co_u32_e32 v172, vcc, 0x118000, v4
	s_nop 1
	v_addc_co_u32_e32 v173, vcc, 0, v5, vcc
	v_add_co_u32_e32 v174, vcc, 0x110000, v4
	s_nop 1
	v_addc_co_u32_e32 v175, vcc, 0, v5, vcc
	v_add_co_u32_e32 v176, vcc, 0x128000, v4
	s_nop 1
	v_addc_co_u32_e32 v177, vcc, 0, v5, vcc
	v_add_co_u32_e32 v178, vcc, 0x120000, v4
	s_nop 1
	v_addc_co_u32_e32 v179, vcc, 0, v5, vcc
	v_add_co_u32_e32 v180, vcc, 0x138000, v4
	s_nop 1
	v_addc_co_u32_e32 v181, vcc, 0, v5, vcc
	v_add_co_u32_e32 v182, vcc, 0x130000, v4
	s_nop 1
	v_addc_co_u32_e32 v183, vcc, 0, v5, vcc
	global_load_dword v185, v[168:169], off
	global_load_dword v186, v[170:171], off
	global_load_dword v187, v[172:173], off
	global_load_dword v188, v[174:175], off
	global_load_dword v190, v[176:177], off
	global_load_dword v191, v[178:179], off
	global_load_dword v192, v[180:181], off
	s_nop 0
	global_load_dword v195, v[182:183], off
	v_add_co_u32_e32 v196, vcc, 0x188000, v4
	s_nop 1
	v_addc_co_u32_e32 v197, vcc, 0, v5, vcc
	v_add_co_u32_e32 v198, vcc, 0x180000, v4
	s_nop 1
	v_addc_co_u32_e32 v199, vcc, 0, v5, vcc
	v_add_co_u32_e32 v200, vcc, 0x198000, v4
	s_nop 1
	v_addc_co_u32_e32 v201, vcc, 0, v5, vcc
	v_add_co_u32_e32 v202, vcc, 0x190000, v4
	s_nop 1
	v_addc_co_u32_e32 v203, vcc, 0, v5, vcc
	v_add_co_u32_e32 v204, vcc, 0x1a8000, v4
	s_nop 1
	v_addc_co_u32_e32 v205, vcc, 0, v5, vcc
	v_add_co_u32_e32 v206, vcc, 0x1a0000, v4
	s_nop 1
	v_addc_co_u32_e32 v207, vcc, 0, v5, vcc
	v_add_co_u32_e32 v208, vcc, 0x1b8000, v4
	s_nop 1
	v_addc_co_u32_e32 v209, vcc, 0, v5, vcc
	v_add_co_u32_e32 v216, vcc, 0x1b0000, v4
	s_nop 1
	v_addc_co_u32_e32 v217, vcc, 0, v5, vcc
	global_load_dword v219, v[196:197], off
	s_nop 0
	global_load_dword v220, v[198:199], off
	global_load_dword v221, v[200:201], off
	s_nop 0
	global_load_dword v222, v[202:203], off
	global_load_dword v223, v[204:205], off
	global_load_dword v224, v[206:207], off
	global_load_dword v225, v[208:209], off
	s_nop 0
	global_load_dword v226, v[216:217], off
	v_lshlrev_b32_e32 v5, 2, v41
	v_lshl_or_b32 v5, v40, 13, v5
	s_waitcnt vmcnt(30)
	v_cvt_pk_bf16_f32 v18, v132, v131
	s_waitcnt vmcnt(28)
	v_cvt_pk_bf16_f32 v19, v135, v133
	s_waitcnt vmcnt(26)
	v_cvt_pk_bf16_f32 v20, v137, v136
	s_waitcnt vmcnt(24)
	v_cvt_pk_bf16_f32 v21, v139, v138
	s_waitcnt vmcnt(22)
	v_cvt_pk_bf16_f32 v22, v158, v157
	s_waitcnt vmcnt(20)
	v_cvt_pk_bf16_f32 v23, v160, v159
	s_waitcnt vmcnt(18)
	v_cvt_pk_bf16_f32 v24, v162, v161
	s_waitcnt vmcnt(16)
	v_cvt_pk_bf16_f32 v25, v167, v164
	s_waitcnt vmcnt(14)
	v_cvt_pk_bf16_f32 v26, v186, v185
	s_waitcnt vmcnt(12)
	v_cvt_pk_bf16_f32 v27, v188, v187
	s_waitcnt vmcnt(10)
	v_cvt_pk_bf16_f32 v28, v191, v190
	s_waitcnt vmcnt(8)
	v_cvt_pk_bf16_f32 v29, v195, v192
	s_waitcnt vmcnt(6)
	v_cvt_pk_bf16_f32 v30, v220, v219
	s_waitcnt vmcnt(4)
	v_cvt_pk_bf16_f32 v31, v222, v221
	s_waitcnt vmcnt(2)
	v_cvt_pk_bf16_f32 v32, v224, v223
	s_waitcnt vmcnt(0)
	v_cvt_pk_bf16_f32 v33, v226, v225
	global_load_dword v3, v5, s[44:45]
	global_load_dword v56, v5, s[46:47]
	v_lshrrev_b32_e32 v4, 6, v48
	v_lshlrev_b32_e32 v5, 21, v40
	v_lshl_or_b32 v34, v41, 10, v5
	v_bitop3_b32 v5, v4, 1, v50 bitop3:0xc8
	v_cmp_gt_u32_e32 vcc, s48, v48
	v_cmp_eq_u32_e64 s[0:1], 0, v5
	v_lshl_add_u64 v[40:41], s[20:21], 0, v[34:35]
	s_and_b64 s[22:23], vcc, s[0:1]
	s_and_saveexec_b64 s[0:1], s[22:23]
	s_cbranch_execz .LBB0_302
	global_store_short v[40:41], v35, off
